# LDS-DMA attention staging: every wave issues five pieces per tile (uniform counted wait), lag waves decide the wait mode before their MFMA half
# baseline (speedup 1.0000x reference)
.LBB0_218:
	s_bfe_u32 s4, s36, 0x30004
	v_lshl_add_u32 v0, s4, 9, v222
	v_ashrrev_i32_e32 v1, 31, v0
	v_lshl_add_u64 v[0:1], v[0:1], 2, s[14:15]
	global_load_dword v232, v[0:1], off
	s_lshl_b32 s5, s36, 6
	s_and_b32 s66, s5, 0x2000
	s_lshl_b32 s5, s21, 7
	s_add_i32 s5, s5, s58
	s_ashr_i32 s8, s5, 31
	s_add_u32 s62, s5, s66
	s_addc_u32 s63, s8, 0
	v_mov_b32_e32 v1, s63
	s_lshl_b32 s89, s4, 7
	s_lshl_b32 s4, s4, 8
	s_mov_b32 s5, s67
	s_mov_b32 s65, s67
	v_lshl_add_u64 v[2:3], s[66:67], 0, v[146:147]
	v_lshlrev_b64 v[2:3], 10, v[2:3]
	v_mov_b32_e32 v5, v3
	v_add_u32_e32 v20, 0, v159
	s_cmp_eq_u32 s21, 0


	v_or_b32_e32 v0, s62, v144
	v_lshlrev_b64 v[0:1], 11, v[0:1]
	v_lshl_add_u64 v[0:1], s[46:47], 0, v[0:1]
	v_lshl_add_u64 v[0:1], v[0:1], 0, s[4:5]
	v_lshl_add_u64 v[0:1], v[0:1], 0, s[64:65]
	v_lshl_add_u64 v[0:1], v[0:1], 0, v[208:209]
	global_load_dwordx4 v[112:115], v[0:1], off
	global_load_dwordx4 v[116:119], v[0:1], off offset:32
	global_load_dwordx4 v[120:123], v[0:1], off offset:64
	global_load_dwordx4 v[124:127], v[0:1], off offset:96
	s_lshl_b32 s4, s66, 11
	s_lshl_b32 s5, s89, 1
	s_add_u32 s4, s4, s5
	s_add_u32 s28, s10, s4
	s_addc_u32 s29, s11, 0
	s_add_u32 s68, s12, s4
	s_addc_u32 s69, s13, 0
	s_lshl_b32 s32, s56, 10
	v_lshlrev_b32_e32 v138, 4, v246
	v_mov_b32_e32 v142, 0xf0f0f1
	v_mov_b32_e32 v143, 0xcccccd
	s_movk_i32 s86, 0x110
	s_movk_i32 s87, 0x140
	v_add_u32_e32 v139, s32, v138
	v_mul_hi_u32 v140, v139, v142
	v_mul_lo_u32 v141, v140, s86
	v_sub_u32_e32 v141, v139, v141
	v_cmp_gt_u32_e32 vcc, 0x100, v141
	s_nop 1
	v_cndmask_b32_e32 v141, 0, v141, vcc
	v_lshl_add_u32 v128, v140, 11, v141
	v_mov_b32_e32 v129, 0
	v_lshl_add_u64 v[128:129], s[28:29], 0, v[128:129]
	s_add_i32 s65, s32, 0x2000
	v_add_u32_e32 v139, s65, v138
	v_mul_hi_u32 v140, v139, v142
	v_mul_lo_u32 v141, v140, s86
	v_sub_u32_e32 v141, v139, v141
	v_cmp_gt_u32_e32 vcc, 0x100, v141
	s_nop 1
	v_cndmask_b32_e32 v141, 0, v141, vcc
	v_lshl_add_u32 v130, v140, 11, v141
	v_mov_b32_e32 v131, 0
	v_lshl_add_u64 v[130:131], s[28:29], 0, v[130:131]
	v_add_u32_e32 v139, s32, v138
	v_mul_hi_u32 v140, v139, v143
	v_mul_lo_u32 v141, v140, s87
	v_sub_u32_e32 v141, v139, v141
	v_cmp_gt_u32_e32 vcc, 0x100, v141
	s_nop 1
	v_cndmask_b32_e32 v141, 0, v141, vcc
	v_lshl_add_u32 v132, v140, 11, v141
	v_mov_b32_e32 v133, 0
	v_lshl_add_u64 v[132:133], s[68:69], 0, v[132:133]
	v_add_u32_e32 v139, s65, v138
	v_mul_hi_u32 v140, v139, v143
	v_mul_lo_u32 v141, v140, s87
	v_sub_u32_e32 v141, v139, v141
	v_cmp_gt_u32_e32 vcc, 0x100, v141
	s_nop 1
	v_cndmask_b32_e32 v141, 0, v141, vcc
	v_lshl_add_u32 v134, v140, 11, v141
	v_mov_b32_e32 v135, 0
	v_lshl_add_u64 v[134:135], s[68:69], 0, v[134:135]
	s_add_i32 s65, s32, 0x3c00
	s_add_i32 s4, s32, 0x2000
	s_cmp_gt_u32 s56, 4
	s_cselect_b32 s65, s4, s65
	s_cmp_eq_u32 s56, 0
	s_cselect_b32 s65, 0x4000, s65
	s_cselect_b32 s86, s86, s87
	s_mov_b32 s87, 0xcccccd
	s_cselect_b32 s87, 0xf0f0f1, s87
	s_cselect_b32 s4, s28, s68
	s_cselect_b32 s5, s29, s69
	v_add_u32_e32 v139, s65, v138
	v_mul_hi_u32 v140, v139, s87
	v_mul_lo_u32 v141, v140, s86
	v_sub_u32_e32 v141, v139, v141
	v_cmp_gt_u32_e32 vcc, 0x100, v141
	s_nop 1
	v_cndmask_b32_e32 v141, 0, v141, vcc
	v_lshl_add_u32 v136, v140, 11, v141
	v_mov_b32_e32 v137, 0
	v_lshl_add_u64 v[136:137], s[4:5], 0, v[136:137]
	s_mov_b32 s28, 0
	s_mov_b32 s29, 0x8800
	s_add_i32 m0, s28, s32
	s_nop 0
	global_load_lds_dwordx4 v[128:129], off
	s_add_i32 m0, m0, 0x2000
	v_lshl_add_u64 v[128:129], v[128:129], 0, s[78:79]
	global_load_lds_dwordx4 v[130:131], off
	v_lshl_add_u64 v[130:131], v[130:131], 0, s[78:79]
	s_cmp_eq_u32 s56, 0
	s_cbranch_scc0 .Ldk_p0
	s_add_i32 m0, s28, 0x4000
	s_nop 0
	global_load_lds_dwordx4 v[136:137], off
	v_lshl_add_u64 v[136:137], v[136:137], 0, s[78:79]
.Ldk_p0:
	s_add_i32 m0, s29, s32
	s_nop 0
	global_load_lds_dwordx4 v[132:133], off
	s_add_i32 m0, m0, 0x2000
	v_lshl_add_u64 v[132:133], v[132:133], 0, s[78:79]
	global_load_lds_dwordx4 v[134:135], off
	v_lshl_add_u64 v[134:135], v[134:135], 0, s[78:79]
	s_cmp_eq_u32 s56, 0
	s_cbranch_scc1 .Ldv_p0
	s_add_i32 m0, s29, s32
	s_mov_b32 vcc_lo, 0x3c00
	s_cmp_gt_u32 s56, 4
	s_cselect_b32 vcc_lo, 0x2000, vcc_lo
	s_add_i32 m0, m0, vcc_lo
	s_nop 0
	global_load_lds_dwordx4 v[136:137], off
	v_lshl_add_u64 v[136:137], v[136:137], 0, s[78:79]

.Ldk_p3:
	s_add_i32 m0, s28, s32
	s_nop 0
	global_load_lds_dwordx4 v[132:133], off
	s_add_i32 m0, m0, 0x2000
	v_lshl_add_u64 v[132:133], v[132:133], 0, s[78:79]
	global_load_lds_dwordx4 v[134:135], off
	v_lshl_add_u64 v[134:135], v[134:135], 0, s[78:79]
	s_cmp_eq_u32 s56, 0
	s_cbranch_scc1 .Ldv_p3
	s_add_i32 m0, s28, s32
	s_mov_b32 vcc_lo, 0x3c00
	s_cmp_gt_u32 s56, 4
	s_cselect_b32 vcc_lo, 0x2000, vcc_lo
	s_add_i32 m0, m0, vcc_lo
	s_nop 0
	global_load_lds_dwordx4 v[136:137], off
	v_lshl_add_u64 v[136:137], v[136:137], 0, s[78:79]

.Ldk_b:
.Latt_b_nok:
	s_add_i32 s4, s29, 0x8800
	s_add_i32 m0, s4, s32
	s_nop 0
	global_load_lds_dwordx4 v[132:133], off
	s_add_i32 m0, m0, 0x2000
	v_lshl_add_u64 v[132:133], v[132:133], 0, s[78:79]
	global_load_lds_dwordx4 v[134:135], off
	v_lshl_add_u64 v[134:135], v[134:135], 0, s[78:79]
	s_cmp_eq_u32 s56, 0
	s_cbranch_scc1 .Ldv_b
	s_add_i32 m0, s4, s32
	s_mov_b32 vcc_lo, 0x3c00
	s_cmp_gt_u32 s56, 4
	s_cselect_b32 vcc_lo, 0x2000, vcc_lo
	s_add_i32 m0, m0, vcc_lo
	s_nop 0
	global_load_lds_dwordx4 v[136:137], off
	v_lshl_add_u64 v[136:137], v[136:137], 0, s[78:79]

.Latt_b_bar:
	s_add_i32 s4, s65, 1
	s_cmp_lt_u32 s4, s66
	s_cbranch_scc0 .Lw0_b
	s_waitcnt vmcnt(5) lgkmcnt(0)
	s_branch .Lwd_b

.Latt_a:
	s_add_i32 s29, s65, 1
	s_cmp_lt_u32 s29, s66
	s_cselect_b32 s29, 1, 0
	s_mul_i32 s4, s87, 0x5000
	v_add_u32_e32 v205, s4, v165
	v_add_u32_e32 v206, s5, v192
	ds_read_b64_tr_b16 v[96:97], v205 offset:34816
	ds_read_b64_tr_b16 v[98:99], v205 offset:37376
	ds_read_b64_tr_b16 v[100:101], v205 offset:39936
	ds_read_b64_tr_b16 v[102:103], v205 offset:42496
	ds_read_b64_tr_b16 v[104:105], v205 offset:45056
	ds_read_b64_tr_b16 v[106:107], v205 offset:47616
	ds_read_b64_tr_b16 v[108:109], v205 offset:50176
	ds_read_b64_tr_b16 v[110:111], v205 offset:52736
	ds_read_b64_tr_b16 v[176:177], v205 offset:34880
	ds_read_b64_tr_b16 v[178:179], v205 offset:37440
	ds_read_b64_tr_b16 v[180:181], v205 offset:40000
	ds_read_b64_tr_b16 v[182:183], v205 offset:42560
	ds_read_b64_tr_b16 v[184:185], v205 offset:45120
	ds_read_b64_tr_b16 v[186:187], v205 offset:47680
	s_setprio 1
	s_waitcnt lgkmcnt(12)
	v_mfma_f32_32x32x16_bf16 v[32:47], v[96:99], v[80:83], v[32:47]
	ds_read_b64_tr_b16 v[96:97], v205 offset:50240
	ds_read_b64_tr_b16 v[98:99], v205 offset:52800
	s_waitcnt lgkmcnt(12)
	v_mfma_f32_32x32x16_bf16 v[32:47], v[100:103], v[84:87], v[32:47]
	ds_read_b64_tr_b16 v[100:101], v205 offset:34944
	ds_read_b64_tr_b16 v[102:103], v205 offset:37504
	s_waitcnt lgkmcnt(12)
	v_mfma_f32_32x32x16_bf16 v[32:47], v[104:107], v[88:91], v[32:47]
	ds_read_b64_tr_b16 v[104:105], v205 offset:40064
	ds_read_b64_tr_b16 v[106:107], v205 offset:42624
	s_waitcnt lgkmcnt(12)
	v_mfma_f32_32x32x16_bf16 v[32:47], v[108:111], v[92:95], v[32:47]
	ds_read_b64_tr_b16 v[108:109], v205 offset:45184
	ds_read_b64_tr_b16 v[110:111], v205 offset:47744
	s_waitcnt lgkmcnt(12)
	v_mfma_f32_32x32x16_bf16 v[16:31], v[176:179], v[80:83], v[16:31]
	ds_read_b64_tr_b16 v[176:177], v205 offset:50304
	ds_read_b64_tr_b16 v[178:179], v205 offset:52864
	s_waitcnt lgkmcnt(12)
	v_mfma_f32_32x32x16_bf16 v[16:31], v[180:183], v[84:87], v[16:31]
	ds_read_b64_tr_b16 v[180:181], v205 offset:35008
	ds_read_b64_tr_b16 v[182:183], v205 offset:37568
	s_waitcnt lgkmcnt(12)
	v_mfma_f32_32x32x16_bf16 v[16:31], v[184:187], v[88:91], v[16:31]
	ds_read_b64_tr_b16 v[184:185], v205 offset:40128
	ds_read_b64_tr_b16 v[186:187], v205 offset:42688
	s_waitcnt lgkmcnt(12)
	v_mfma_f32_32x32x16_bf16 v[16:31], v[96:99], v[92:95], v[16:31]
	ds_read_b64_tr_b16 v[96:97], v205 offset:45248
	ds_read_b64_tr_b16 v[98:99], v205 offset:47808
	s_waitcnt lgkmcnt(12)
	v_mfma_f32_32x32x16_bf16 v[0:15], v[100:103], v[80:83], v[0:15]
	ds_read_b64_tr_b16 v[100:101], v205 offset:50368
	ds_read_b64_tr_b16 v[102:103], v205 offset:52928
	s_waitcnt lgkmcnt(12)
	v_mfma_f32_32x32x16_bf16 v[0:15], v[104:107], v[84:87], v[0:15]
	ds_read_b128 v[210:213], v206 offset:8704
	ds_read_b128 v[104:107], v206 offset:8736
	s_waitcnt lgkmcnt(12)
	v_mfma_f32_32x32x16_bf16 v[0:15], v[108:111], v[88:91], v[0:15]
	ds_read_b128 v[108:111], v206 offset:8768
	ds_read_b128 v[188:191], v206
	s_waitcnt lgkmcnt(12)
	v_mfma_f32_32x32x16_bf16 v[0:15], v[176:179], v[92:95], v[0:15]
	ds_read_b128 v[176:179], v206 offset:8800
	ds_read_b128 v[224:227], v206 offset:32
	s_waitcnt lgkmcnt(12)
	v_mfma_f32_32x32x16_bf16 v[48:63], v[180:183], v[80:83], v[48:63]
	ds_read_b128 v[228:231], v206 offset:64
	ds_read_b128 v[248:251], v206 offset:96
	s_waitcnt lgkmcnt(12)
	v_mfma_f32_32x32x16_bf16 v[48:63], v[184:187], v[84:87], v[48:63]
	s_waitcnt lgkmcnt(10)
	v_mfma_f32_32x32x16_bf16 v[48:63], v[96:99], v[88:91], v[48:63]
	s_waitcnt lgkmcnt(8)
	v_mfma_f32_32x32x16_bf16 v[48:63], v[100:103], v[92:95], v[48:63]
	s_waitcnt lgkmcnt(7)
	v_mfma_f32_32x32x16_bf16 v[80:95], v[210:213], v[112:115], v[64:79]
	s_waitcnt lgkmcnt(6)
	v_mfma_f32_32x32x16_bf16 v[80:95], v[104:107], v[116:119], v[80:95]
	s_waitcnt lgkmcnt(5)
	v_mfma_f32_32x32x16_bf16 v[80:95], v[108:111], v[120:123], v[80:95]
	s_waitcnt lgkmcnt(3)
	v_mfma_f32_32x32x16_bf16 v[80:95], v[176:179], v[124:127], v[80:95]
	s_waitcnt lgkmcnt(4)
	v_mfma_f32_32x32x16_bf16 v[96:111], v[188:191], v[112:115], v[64:79]
	s_waitcnt lgkmcnt(2)
	v_mfma_f32_32x32x16_bf16 v[96:111], v[224:227], v[116:119], v[96:111]
	s_waitcnt lgkmcnt(1)
	v_mfma_f32_32x32x16_bf16 v[96:111], v[228:231], v[120:123], v[96:111]
	s_waitcnt lgkmcnt(0)
	v_mfma_f32_32x32x16_bf16 v[96:111], v[248:251], v[124:127], v[96:111]
	s_setprio 0
	s_cmp_gt_i32 s33, 2
	s_cbranch_scc1 .Latt_a_stg
	s_waitcnt lgkmcnt(0)
	v_add_u32_e32 v205, s68, v204
	v_add_u32_e32 v176, 0x17d00, v205
	v_add_u32_e32 v178, 0x17d80, v205
	ds_read2_b32 v[176:177], v176 offset1:1
	ds_read2_b32 v[178:179], v178 offset1:1
	v_add_u32_e32 v180, 0x17d08, v205
	v_add_u32_e32 v182, 0x17d88, v205
	v_add_u32_e32 v184, 0x17d20, v205
	v_add_u32_e32 v186, 0x17da0, v205
	v_add_u32_e32 v188, 0x17d28, v205
	v_add_u32_e32 v190, 0x17da8, v205
	v_add_u32_e32 v206, 0x17d40, v205
	v_add_u32_e32 v210, 0x17dc0, v205
	v_add_u32_e32 v212, 0x17d48, v205
	v_add_u32_e32 v221, 0x17dc8, v205
	ds_read2_b32 v[180:181], v180 offset1:1
	ds_read2_b32 v[182:183], v182 offset1:1
	ds_read2_b32 v[184:185], v184 offset1:1
	ds_read2_b32 v[186:187], v186 offset1:1
	ds_read2_b32 v[188:189], v188 offset1:1
	ds_read2_b32 v[190:191], v190 offset1:1
	ds_read2_b32 v[206:207], v206 offset1:1
	ds_read2_b32 v[210:211], v210 offset1:1
	ds_read2_b32 v[212:213], v212 offset1:1
	ds_read2_b32 v[224:225], v221 offset1:1
	v_add_u32_e32 v221, 0x17d60, v205
	v_add_u32_e32 v223, 0x17de0, v205
	ds_read2_b32 v[226:227], v221 offset1:1
	ds_read2_b32 v[228:229], v223 offset1:1
	v_add_u32_e32 v221, 0x17d68, v205
	v_add_u32_e32 v205, 0x17de8, v205
	ds_read2_b32 v[230:231], v221 offset1:1
	s_waitcnt lgkmcnt(14)
	v_pk_add_f32 v[96:97], v[96:97], v[176:177]
	ds_read2_b32 v[176:177], v205 offset1:1
	s_waitcnt lgkmcnt(3)
	v_pk_add_f32 v[108:109], v[108:109], v[226:227]
	v_pk_add_f32 v[106:107], v[106:107], v[212:213]
	s_waitcnt lgkmcnt(1)
	v_pk_add_f32 v[110:111], v[110:111], v[230:231]
	v_pk_add_f32 v[104:105], v[104:105], v[206:207]
	v_pk_add_f32 v[102:103], v[102:103], v[188:189]
	v_pk_add_f32 v[100:101], v[100:101], v[184:185]
	v_pk_add_f32 v[98:99], v[98:99], v[180:181]
	s_waitcnt lgkmcnt(0)
	v_pk_add_f32 v[94:95], v[94:95], v[176:177]
	v_pk_add_f32 v[92:93], v[92:93], v[228:229]
	v_pk_add_f32 v[90:91], v[90:91], v[224:225]
	v_pk_add_f32 v[88:89], v[88:89], v[210:211]
	v_pk_add_f32 v[86:87], v[86:87], v[190:191]
	v_pk_add_f32 v[84:85], v[84:85], v[186:187]
	v_pk_add_f32 v[82:83], v[82:83], v[182:183]
	v_pk_add_f32 v[80:81], v[80:81], v[178:179]
	s_nop 0
.Latt_a_stg:
.Latt_a_bar:
	s_cmp_eq_u32 s29, 0
	s_cbranch_scc1 .Lw0_a
	s_waitcnt vmcnt(5) lgkmcnt(0)
	s_barrier
	s_branch .Lwd_a

.Lwd_a:
	s_add_i32 s4, s65, 1
	s_cmp_ge_u32 s4, s66
	s_cbranch_scc1 .Latt_a_nod
	s_add_i32 s4, s65, 2
	s_cmp_ge_u32 s4, s66
	s_cbranch_scc1 .Latt_a_nok
	s_add_i32 m0, s5, s32
	s_nop 0
	global_load_lds_dwordx4 v[128:129], off
	s_add_i32 m0, m0, 0x2000
	v_lshl_add_u64 v[128:129], v[128:129], 0, s[78:79]
	global_load_lds_dwordx4 v[130:131], off
	v_lshl_add_u64 v[130:131], v[130:131], 0, s[78:79]
	s_cmp_eq_u32 s56, 0
	s_cbranch_scc0 .Ldk_a
	s_add_i32 m0, s5, 0x4000
	s_nop 0
	global_load_lds_dwordx4 v[136:137], off
	v_lshl_add_u64 v[136:137], v[136:137], 0, s[78:79]
.Ldk_a:
.Latt_a_nok:
	s_mul_i32 s29, s87, 0x5000
	s_add_i32 s29, s29, 0x8800
	s_add_i32 m0, s29, s32
	s_nop 0
	global_load_lds_dwordx4 v[132:133], off
	s_add_i32 m0, m0, 0x2000
	v_lshl_add_u64 v[132:133], v[132:133], 0, s[78:79]
	global_load_lds_dwordx4 v[134:135], off
	v_lshl_add_u64 v[134:135], v[134:135], 0, s[78:79]
	s_cmp_eq_u32 s56, 0
	s_cbranch_scc1 .Ldv_a
	s_add_i32 m0, s29, s32
	s_mov_b32 vcc_lo, 0x3c00
	s_cmp_gt_u32 s56, 4
	s_cselect_b32 vcc_lo, 0x2000, vcc_lo
	s_add_i32 m0, m0, vcc_lo
	s_nop 0
	global_load_lds_dwordx4 v[136:137], off
	v_lshl_add_u64 v[136:137], v[136:137], 0, s[78:79]
